# sample-row GEMM K loops (4 phases): all 20 fragment loads per iteration issued up front with own registers, counted waits
# baseline (speedup 1.0000x reference)
.LBB0_141:
	v_lshl_add_u64 v[82:83], v[70:71], 0, s[0:1]
	v_add_co_u32_e32 v90, vcc, s5, v82
	v_lshl_add_u64 v[126:127], v[72:73], 0, s[0:1]
	s_nop 1
	v_addc_co_u32_e32 v91, vcc, 0, v83, vcc
	v_add_co_u32_e32 v102, vcc, s6, v82
	s_add_u32 s0, s0, 0x80
	s_nop 1
	v_addc_co_u32_e32 v103, vcc, 0, v83, vcc
	v_add_co_u32_e32 v94, vcc, s7, v126
	s_addc_u32 s1, s1, 0
	s_nop 1
	v_addc_co_u32_e32 v95, vcc, 0, v127, vcc
	v_add_co_u32_e32 v106, vcc, s8, v126
	s_cmpk_eq_i32 s0, 0x100
	s_nop 1
	v_addc_co_u32_e32 v107, vcc, 0, v127, vcc
	v_add_co_u32_e32 v110, vcc, s9, v126
	s_nop 1
	v_addc_co_u32_e32 v111, vcc, 0, v127, vcc
	v_add_co_u32_e32 v114, vcc, s10, v126
	s_nop 1
	v_addc_co_u32_e32 v115, vcc, 0, v127, vcc
	v_add_co_u32_e32 v118, vcc, s11, v126
	s_nop 1
	v_addc_co_u32_e32 v119, vcc, 0, v127, vcc
	v_add_co_u32_e32 v122, vcc, s12, v126
	s_nop 1
	v_addc_co_u32_e32 v123, vcc, 0, v127, vcc
	v_add_co_u32_e32 v128, vcc, s13, v126
	s_nop 1
	v_addc_co_u32_e32 v129, vcc, 0, v127, vcc
	v_add_co_u32_e32 v134, vcc, s14, v126
	s_nop 1
	v_addc_co_u32_e32 v135, vcc, 0, v127, vcc
	global_load_dwordx4 v[82:85], v[90:91], off
	global_load_dwordx4 v[86:89], v[94:95], off
	global_load_dwordx4 v[90:93], v[90:91], off offset:64
	global_load_dwordx4 v[94:97], v[94:95], off offset:64
	global_load_dwordx4 v[98:101], v[102:103], off
	global_load_dwordx4 v[102:105], v[102:103], off offset:64
	global_load_dwordx4 v[216:219], v[106:107], off
	global_load_dwordx4 v[106:109], v[106:107], off offset:64
	global_load_dwordx4 v[220:223], v[110:111], off
	global_load_dwordx4 v[110:113], v[110:111], off offset:64
	global_load_dwordx4 v[224:227], v[114:115], off
	global_load_dwordx4 v[114:117], v[114:115], off offset:64
	global_load_dwordx4 v[232:235], v[118:119], off
	global_load_dwordx4 v[118:121], v[118:119], off offset:64
	global_load_dwordx4 v[236:239], v[122:123], off
	global_load_dwordx4 v[122:125], v[122:123], off offset:64
	global_load_dwordx4 v[240:243], v[128:129], off
	global_load_dwordx4 v[126:129], v[128:129], off offset:64
	global_load_dwordx4 v[130:133], v[134:135], off
	global_load_dwordx4 v[244:247], v[134:135], off offset:64
	s_waitcnt vmcnt(18)
	v_mfma_f32_16x16x32_bf16 v[56:59], v[82:85], v[86:89], v[56:59]
	s_waitcnt vmcnt(15)
	v_mfma_f32_16x16x32_bf16 v[52:55], v[98:101], v[86:89], v[52:55]
	v_mfma_f32_16x16x32_bf16 v[56:59], v[90:93], v[94:97], v[56:59]
	s_waitcnt vmcnt(14)
	v_mfma_f32_16x16x32_bf16 v[52:55], v[102:105], v[94:97], v[52:55]
	s_waitcnt vmcnt(13)
	v_mfma_f32_16x16x32_bf16 v[40:43], v[82:85], v[216:219], v[40:43]
	v_mfma_f32_16x16x32_bf16 v[16:19], v[98:101], v[216:219], v[16:19]
	s_waitcnt vmcnt(12)
	v_mfma_f32_16x16x32_bf16 v[40:43], v[90:93], v[106:109], v[40:43]
	v_mfma_f32_16x16x32_bf16 v[16:19], v[102:105], v[106:109], v[16:19]
	s_waitcnt vmcnt(11)
	v_mfma_f32_16x16x32_bf16 v[12:15], v[82:85], v[220:223], v[12:15]
	v_mfma_f32_16x16x32_bf16 v[8:11], v[98:101], v[220:223], v[8:11]
	s_waitcnt vmcnt(10)
	v_mfma_f32_16x16x32_bf16 v[12:15], v[90:93], v[110:113], v[12:15]
	v_mfma_f32_16x16x32_bf16 v[8:11], v[102:105], v[110:113], v[8:11]
	s_waitcnt vmcnt(9)
	v_mfma_f32_16x16x32_bf16 v[4:7], v[82:85], v[224:227], v[4:7]
	v_mfma_f32_16x16x32_bf16 v[0:3], v[98:101], v[224:227], v[0:3]
	s_waitcnt vmcnt(8)
	v_mfma_f32_16x16x32_bf16 v[4:7], v[90:93], v[114:117], v[4:7]
	v_mfma_f32_16x16x32_bf16 v[0:3], v[102:105], v[114:117], v[0:3]
	s_waitcnt vmcnt(7)
	v_mfma_f32_16x16x32_bf16 v[20:23], v[82:85], v[232:235], v[20:23]
	v_mfma_f32_16x16x32_bf16 v[24:27], v[98:101], v[232:235], v[24:27]
	s_waitcnt vmcnt(6)
	v_mfma_f32_16x16x32_bf16 v[20:23], v[90:93], v[118:121], v[20:23]
	v_mfma_f32_16x16x32_bf16 v[24:27], v[102:105], v[118:121], v[24:27]
	s_waitcnt vmcnt(5)
	v_mfma_f32_16x16x32_bf16 v[28:31], v[82:85], v[236:239], v[28:31]
	v_mfma_f32_16x16x32_bf16 v[32:35], v[98:101], v[236:239], v[32:35]
	s_waitcnt vmcnt(4)
	v_mfma_f32_16x16x32_bf16 v[28:31], v[90:93], v[122:125], v[28:31]
	v_mfma_f32_16x16x32_bf16 v[32:35], v[102:105], v[122:125], v[32:35]
	s_waitcnt vmcnt(3)
	v_mfma_f32_16x16x32_bf16 v[36:39], v[82:85], v[240:243], v[36:39]
	v_mfma_f32_16x16x32_bf16 v[44:47], v[98:101], v[240:243], v[44:47]
	s_waitcnt vmcnt(1)
	v_mfma_f32_16x16x32_bf16 v[48:51], v[82:85], v[130:133], v[48:51]
	v_mfma_f32_16x16x32_bf16 v[60:63], v[98:101], v[130:133], v[60:63]
	v_mfma_f32_16x16x32_bf16 v[36:39], v[90:93], v[126:129], v[36:39]
	v_mfma_f32_16x16x32_bf16 v[44:47], v[102:105], v[126:129], v[44:47]
	s_waitcnt vmcnt(0)
	v_mfma_f32_16x16x32_bf16 v[48:51], v[90:93], v[244:247], v[48:51]
	v_mfma_f32_16x16x32_bf16 v[60:63], v[102:105], v[244:247], v[60:63]
	s_cbranch_scc0 .LBB0_141
	v_add_u32_e32 v66, s2, v75
	s_waitcnt lgkmcnt(0)
	s_barrier
	ds_write_b128 v66, v[56:59]
	ds_write_b128 v66, v[52:55] offset:1024
	ds_write_b128 v66, v[40:43] offset:2048
	ds_write_b128 v66, v[16:19] offset:3072
	ds_write_b128 v66, v[12:15] offset:4096
	ds_write_b128 v66, v[8:11] offset:5120
	ds_write_b128 v66, v[4:7] offset:6144
	ds_write_b128 v66, v[0:3] offset:7168
	ds_write_b128 v66, v[20:23] offset:8192
	ds_write_b128 v66, v[24:27] offset:9216
	ds_write_b128 v66, v[28:31] offset:10240
	ds_write_b128 v66, v[32:35] offset:11264
	ds_write_b128 v66, v[36:39] offset:12288
	ds_write_b128 v66, v[44:47] offset:13312
	ds_write_b128 v66, v[48:51] offset:14336
	ds_write_b128 v66, v[60:63] offset:15360
	s_waitcnt lgkmcnt(0)
	s_barrier
	v_add_u32_e32 v22, s3, v75
	ds_read_b128 v[0:3], v22
	ds_read_b128 v[4:7], v22 offset:16384
	ds_read_b128 v[8:11], v22 offset:32768
	ds_read_b128 v[12:15], v22 offset:1024
	ds_read_b128 v[16:19], v22 offset:17408
	s_mulk_i32 s16, 0xb0
	s_sub_i32 s0, s15, s16
	v_lshl_or_b32 v28, s0, 5, v76
	s_waitcnt lgkmcnt(3)
	v_pk_add_f32 v[6:7], v[2:3], v[6:7]
	v_pk_add_f32 v[20:21], v[0:1], v[4:5]
	ds_read_b128 v[0:3], v22 offset:33792
	s_waitcnt lgkmcnt(3)
	v_pk_add_f32 v[24:25], v[6:7], v[10:11]
	ds_read_b128 v[4:7], v22 offset:49152
	v_pk_add_f32 v[26:27], v[20:21], v[8:9]
	v_add_u32_e32 v8, s3, v77
	ds_read_b128 v[8:11], v8
	ds_read_b128 v[20:23], v22 offset:50176
	v_ashrrev_i32_e32 v29, 31, v28
	s_waitcnt lgkmcnt(2)
	v_pk_add_f32 v[26:27], v[26:27], v[4:5]
	v_add_u32_e32 v4, s3, v78
	v_pk_add_f32 v[24:25], v[24:25], v[6:7]
	ds_read_b128 v[4:7], v4
	s_waitcnt lgkmcnt(2)
	v_pk_add_f32 v[32:33], v[26:27], v[8:9]
	v_add_u32_e32 v8, s3, v79
	v_pk_add_f32 v[30:31], v[24:25], v[10:11]
	ds_read_b128 v[8:11], v8
	v_add_u32_e32 v24, s3, v80
	ds_read_b128 v[24:27], v24
	s_waitcnt lgkmcnt(2)
	v_pk_add_f32 v[6:7], v[30:31], v[6:7]
	v_pk_add_f32 v[4:5], v[32:33], v[4:5]
	s_waitcnt lgkmcnt(1)
	v_pk_add_f32 v[6:7], v[6:7], v[10:11]
	v_pk_add_f32 v[4:5], v[4:5], v[8:9]
	s_waitcnt lgkmcnt(0)
	v_pk_add_f32 v[6:7], v[6:7], v[26:27]
	v_pk_add_f32 v[4:5], v[4:5], v[24:25]
	v_lshl_add_u64 v[24:25], v[28:29], 1, v[64:65]
	v_cvt_pk_bf16_f32 v4, v4, v5
	v_cvt_pk_bf16_f32 v5, v6, v7
	v_pk_add_f32 v[6:7], v[12:13], v[16:17]
	global_store_dwordx2 v[24:25], v[4:5], off
	v_pk_add_f32 v[4:5], v[14:15], v[18:19]
	v_pk_add_f32 v[6:7], v[6:7], v[0:1]
	v_add_u32_e32 v0, s4, v77
	v_pk_add_f32 v[4:5], v[4:5], v[2:3]
	ds_read_b128 v[0:3], v0
	v_pk_add_f32 v[8:9], v[4:5], v[22:23]
	v_pk_add_f32 v[10:11], v[6:7], v[20:21]
	v_add_u32_e32 v4, s4, v78
	ds_read_b128 v[4:7], v4
	s_waitcnt lgkmcnt(1)
	v_pk_add_f32 v[14:15], v[10:11], v[0:1]
	v_add_u32_e32 v0, s4, v79
	v_pk_add_f32 v[12:13], v[8:9], v[2:3]
	ds_read_b128 v[0:3], v0
	v_add_u32_e32 v8, s4, v80
	ds_read_b128 v[8:11], v8
	s_waitcnt lgkmcnt(2)
	v_pk_add_f32 v[6:7], v[12:13], v[6:7]
	v_pk_add_f32 v[4:5], v[14:15], v[4:5]
	s_waitcnt lgkmcnt(1)
	v_pk_add_f32 v[2:3], v[6:7], v[2:3]
	v_pk_add_f32 v[0:1], v[4:5], v[0:1]
	s_waitcnt lgkmcnt(0)
	v_pk_add_f32 v[2:3], v[2:3], v[10:11]
	v_pk_add_f32 v[0:1], v[0:1], v[8:9]
	s_add_i32 s15, s15, s52
	v_cvt_pk_bf16_f32 v0, v0, v1
	v_cvt_pk_bf16_f32 v1, v2, v3
	s_cmpk_gt_i32 s15, 0xaf
	global_store_dwordx2 v[24:25], v[0:1], off offset:32
	s_cbranch_scc0 .LBB0_140

.LBB0_350:
	v_lshl_add_u64 v[82:83], v[70:71], 0, s[0:1]
	v_add_co_u32_e32 v98, vcc, s7, v82
	v_lshl_add_u64 v[126:127], v[72:73], 0, s[0:1]
	s_nop 1
	v_addc_co_u32_e32 v99, vcc, 0, v83, vcc
	v_add_co_u32_e32 v106, vcc, s8, v82
	s_add_u32 s0, s0, 0x80
	s_nop 1
	v_addc_co_u32_e32 v107, vcc, 0, v83, vcc
	v_add_co_u32_e32 v100, vcc, s9, v126
	s_addc_u32 s1, s1, 0
	s_nop 1
	v_addc_co_u32_e32 v101, vcc, 0, v127, vcc
	v_add_co_u32_e32 v110, vcc, s10, v126
	s_cmpk_eq_i32 s0, 0x100
	s_nop 1
	v_addc_co_u32_e32 v111, vcc, 0, v127, vcc
	v_add_co_u32_e32 v114, vcc, s11, v126
	s_nop 1
	v_addc_co_u32_e32 v115, vcc, 0, v127, vcc
	v_add_co_u32_e32 v118, vcc, s12, v126
	s_nop 1
	v_addc_co_u32_e32 v119, vcc, 0, v127, vcc
	v_add_co_u32_e32 v120, vcc, s13, v126
	s_nop 1
	v_addc_co_u32_e32 v121, vcc, 0, v127, vcc
	v_add_co_u32_e32 v122, vcc, s14, v126
	s_nop 1
	v_addc_co_u32_e32 v123, vcc, 0, v127, vcc
	v_add_co_u32_e32 v128, vcc, s15, v126
	s_nop 1
	v_addc_co_u32_e32 v129, vcc, 0, v127, vcc
	v_add_co_u32_e32 v134, vcc, s16, v126
	s_nop 1
	v_addc_co_u32_e32 v135, vcc, 0, v127, vcc
	global_load_dwordx4 v[82:85], v[98:99], off
	global_load_dwordx4 v[86:89], v[100:101], off
	global_load_dwordx4 v[90:93], v[98:99], off offset:64
	global_load_dwordx4 v[94:97], v[100:101], off offset:64
	global_load_dwordx4 v[98:101], v[106:107], off
	global_load_dwordx4 v[102:105], v[106:107], off offset:64
	global_load_dwordx4 v[216:219], v[110:111], off
	global_load_dwordx4 v[106:109], v[110:111], off offset:64
	global_load_dwordx4 v[220:223], v[114:115], off
	global_load_dwordx4 v[110:113], v[114:115], off offset:64
	global_load_dwordx4 v[224:227], v[118:119], off
	global_load_dwordx4 v[114:117], v[118:119], off offset:64
	global_load_dwordx4 v[234:237], v[120:121], off
	global_load_dwordx4 v[118:121], v[120:121], off offset:64
	global_load_dwordx4 v[238:241], v[122:123], off
	global_load_dwordx4 v[122:125], v[122:123], off offset:64
	global_load_dwordx4 v[242:245], v[128:129], off
	global_load_dwordx4 v[126:129], v[128:129], off offset:64
	global_load_dwordx4 v[130:133], v[134:135], off
	global_load_dwordx4 v[246:249], v[134:135], off offset:64
	s_waitcnt vmcnt(18)
	v_mfma_f32_16x16x32_bf16 v[56:59], v[82:85], v[86:89], v[56:59]
	s_waitcnt vmcnt(15)
	v_mfma_f32_16x16x32_bf16 v[52:55], v[98:101], v[86:89], v[52:55]
	v_mfma_f32_16x16x32_bf16 v[56:59], v[90:93], v[94:97], v[56:59]
	s_waitcnt vmcnt(14)
	v_mfma_f32_16x16x32_bf16 v[52:55], v[102:105], v[94:97], v[52:55]
	s_waitcnt vmcnt(13)
	v_mfma_f32_16x16x32_bf16 v[44:47], v[82:85], v[216:219], v[44:47]
	v_mfma_f32_16x16x32_bf16 v[20:23], v[98:101], v[216:219], v[20:23]
	s_waitcnt vmcnt(12)
	v_mfma_f32_16x16x32_bf16 v[44:47], v[90:93], v[106:109], v[44:47]
	v_mfma_f32_16x16x32_bf16 v[20:23], v[102:105], v[106:109], v[20:23]
	s_waitcnt vmcnt(11)
	v_mfma_f32_16x16x32_bf16 v[12:15], v[82:85], v[220:223], v[12:15]
	v_mfma_f32_16x16x32_bf16 v[8:11], v[98:101], v[220:223], v[8:11]
	s_waitcnt vmcnt(10)
	v_mfma_f32_16x16x32_bf16 v[12:15], v[90:93], v[110:113], v[12:15]
	v_mfma_f32_16x16x32_bf16 v[8:11], v[102:105], v[110:113], v[8:11]
	s_waitcnt vmcnt(9)
	v_mfma_f32_16x16x32_bf16 v[4:7], v[82:85], v[224:227], v[4:7]
	v_mfma_f32_16x16x32_bf16 v[0:3], v[98:101], v[224:227], v[0:3]
	s_waitcnt vmcnt(8)
	v_mfma_f32_16x16x32_bf16 v[4:7], v[90:93], v[114:117], v[4:7]
	v_mfma_f32_16x16x32_bf16 v[0:3], v[102:105], v[114:117], v[0:3]
	s_waitcnt vmcnt(7)
	v_mfma_f32_16x16x32_bf16 v[16:19], v[82:85], v[234:237], v[16:19]
	v_mfma_f32_16x16x32_bf16 v[24:27], v[98:101], v[234:237], v[24:27]
	s_waitcnt vmcnt(6)
	v_mfma_f32_16x16x32_bf16 v[16:19], v[90:93], v[118:121], v[16:19]
	v_mfma_f32_16x16x32_bf16 v[24:27], v[102:105], v[118:121], v[24:27]
	s_waitcnt vmcnt(5)
	v_mfma_f32_16x16x32_bf16 v[28:31], v[82:85], v[238:241], v[28:31]
	v_mfma_f32_16x16x32_bf16 v[32:35], v[98:101], v[238:241], v[32:35]
	s_waitcnt vmcnt(4)
	v_mfma_f32_16x16x32_bf16 v[28:31], v[90:93], v[122:125], v[28:31]
	v_mfma_f32_16x16x32_bf16 v[32:35], v[102:105], v[122:125], v[32:35]
	s_waitcnt vmcnt(3)
	v_mfma_f32_16x16x32_bf16 v[36:39], v[82:85], v[242:245], v[36:39]
	v_mfma_f32_16x16x32_bf16 v[40:43], v[98:101], v[242:245], v[40:43]
	s_waitcnt vmcnt(1)
	v_mfma_f32_16x16x32_bf16 v[48:51], v[82:85], v[130:133], v[48:51]
	v_mfma_f32_16x16x32_bf16 v[60:63], v[98:101], v[130:133], v[60:63]
	v_mfma_f32_16x16x32_bf16 v[36:39], v[90:93], v[126:129], v[36:39]
	v_mfma_f32_16x16x32_bf16 v[40:43], v[102:105], v[126:129], v[40:43]
	s_waitcnt vmcnt(0)
	v_mfma_f32_16x16x32_bf16 v[48:51], v[90:93], v[246:249], v[48:51]
	v_mfma_f32_16x16x32_bf16 v[60:63], v[102:105], v[246:249], v[60:63]
	s_cbranch_scc0 .LBB0_350
	v_add_u32_e32 v66, s4, v75
	s_waitcnt lgkmcnt(0)
	s_barrier
	ds_write_b128 v66, v[56:59]
	ds_write_b128 v66, v[52:55] offset:1024
	ds_write_b128 v66, v[44:47] offset:2048
	ds_write_b128 v66, v[20:23] offset:3072
	ds_write_b128 v66, v[12:15] offset:4096
	ds_write_b128 v66, v[8:11] offset:5120
	ds_write_b128 v66, v[4:7] offset:6144
	ds_write_b128 v66, v[0:3] offset:7168
	ds_write_b128 v66, v[16:19] offset:8192
	ds_write_b128 v66, v[24:27] offset:9216
	ds_write_b128 v66, v[28:31] offset:10240
	ds_write_b128 v66, v[32:35] offset:11264
	ds_write_b128 v66, v[36:39] offset:12288
	ds_write_b128 v66, v[40:43] offset:13312
	ds_write_b128 v66, v[48:51] offset:14336
	ds_write_b128 v66, v[60:63] offset:15360
	s_waitcnt lgkmcnt(0)
	s_barrier
	v_add_u32_e32 v22, s5, v75
	ds_read_b128 v[0:3], v22
	ds_read_b128 v[4:7], v22 offset:16384
	ds_read_b128 v[8:11], v22 offset:32768
	ds_read_b128 v[12:15], v22 offset:1024
	ds_read_b128 v[16:19], v22 offset:17408
	s_lshl_b32 s0, s17, 5
	s_sub_i32 s0, s3, s0
	v_lshl_or_b32 v28, s0, 5, v76
	s_waitcnt lgkmcnt(3)
	v_pk_add_f32 v[6:7], v[2:3], v[6:7]
	v_pk_add_f32 v[20:21], v[0:1], v[4:5]
	ds_read_b128 v[0:3], v22 offset:33792
	s_waitcnt lgkmcnt(3)
	v_pk_add_f32 v[24:25], v[6:7], v[10:11]
	ds_read_b128 v[4:7], v22 offset:49152
	v_pk_add_f32 v[26:27], v[20:21], v[8:9]
	v_add_u32_e32 v8, s5, v77
	ds_read_b128 v[8:11], v8
	ds_read_b128 v[20:23], v22 offset:50176
	v_ashrrev_i32_e32 v29, 31, v28
	s_waitcnt lgkmcnt(2)
	v_pk_add_f32 v[26:27], v[26:27], v[4:5]
	v_add_u32_e32 v4, s5, v78
	v_pk_add_f32 v[24:25], v[24:25], v[6:7]
	ds_read_b128 v[4:7], v4
	s_waitcnt lgkmcnt(2)
	v_pk_add_f32 v[32:33], v[26:27], v[8:9]
	v_add_u32_e32 v8, s5, v79
	v_pk_add_f32 v[30:31], v[24:25], v[10:11]
	ds_read_b128 v[8:11], v8
	v_add_u32_e32 v24, s5, v80
	ds_read_b128 v[24:27], v24
	s_waitcnt lgkmcnt(2)
	v_pk_add_f32 v[6:7], v[30:31], v[6:7]
	v_pk_add_f32 v[4:5], v[32:33], v[4:5]
	s_waitcnt lgkmcnt(1)
	v_pk_add_f32 v[6:7], v[6:7], v[10:11]
	v_pk_add_f32 v[4:5], v[4:5], v[8:9]
	s_waitcnt lgkmcnt(0)
	v_pk_add_f32 v[6:7], v[6:7], v[26:27]
	v_pk_add_f32 v[4:5], v[4:5], v[24:25]
	v_lshl_add_u64 v[24:25], v[28:29], 2, v[64:65]
	global_store_dwordx4 v[24:25], v[4:7], off
	s_add_i32 s3, s3, s2
	s_cmp_gt_i32 s3, 31
	v_pk_add_f32 v[6:7], v[12:13], v[16:17]
	v_pk_add_f32 v[4:5], v[14:15], v[18:19]
	v_pk_add_f32 v[6:7], v[6:7], v[0:1]
	v_add_u32_e32 v0, s6, v77
	v_pk_add_f32 v[4:5], v[4:5], v[2:3]
	ds_read_b128 v[0:3], v0
	v_pk_add_f32 v[8:9], v[4:5], v[22:23]
	v_pk_add_f32 v[10:11], v[6:7], v[20:21]
	v_add_u32_e32 v4, s6, v78
	ds_read_b128 v[4:7], v4
	s_waitcnt lgkmcnt(1)
	v_pk_add_f32 v[14:15], v[10:11], v[0:1]
	v_add_u32_e32 v0, s6, v79
	v_pk_add_f32 v[12:13], v[8:9], v[2:3]
	ds_read_b128 v[0:3], v0
	v_add_u32_e32 v8, s6, v80
	ds_read_b128 v[8:11], v8
	s_waitcnt lgkmcnt(2)
	v_pk_add_f32 v[6:7], v[12:13], v[6:7]
	v_pk_add_f32 v[4:5], v[14:15], v[4:5]
	s_waitcnt lgkmcnt(1)
	v_pk_add_f32 v[2:3], v[6:7], v[2:3]
	v_pk_add_f32 v[0:1], v[4:5], v[0:1]
	s_waitcnt lgkmcnt(0)
	v_pk_add_f32 v[2:3], v[2:3], v[10:11]
	v_pk_add_f32 v[0:1], v[0:1], v[8:9]
	global_store_dwordx4 v[24:25], v[0:3], off offset:64
	s_cbranch_scc0 .LBB0_349

.LBB0_522:
	v_lshl_add_u64 v[84:85], v[72:73], 0, s[0:1]
	v_add_co_u32_e32 v100, vcc, s5, v84
	v_lshl_add_u64 v[128:129], v[74:75], 0, s[0:1]
	s_nop 1
	v_addc_co_u32_e32 v101, vcc, 0, v85, vcc
	v_add_co_u32_e32 v108, vcc, s6, v84
	s_add_u32 s0, s0, 0x80
	s_nop 1
	v_addc_co_u32_e32 v109, vcc, 0, v85, vcc
	v_add_co_u32_e32 v102, vcc, s7, v128
	s_addc_u32 s1, s1, 0
	s_nop 1
	v_addc_co_u32_e32 v103, vcc, 0, v129, vcc
	v_add_co_u32_e32 v112, vcc, s8, v128
	s_cmpk_eq_i32 s0, 0x100
	s_nop 1
	v_addc_co_u32_e32 v113, vcc, 0, v129, vcc
	v_add_co_u32_e32 v116, vcc, s9, v128
	s_nop 1
	v_addc_co_u32_e32 v117, vcc, 0, v129, vcc
	v_add_co_u32_e32 v120, vcc, s10, v128
	s_nop 1
	v_addc_co_u32_e32 v121, vcc, 0, v129, vcc
	v_add_co_u32_e32 v122, vcc, s11, v128
	s_nop 1
	v_addc_co_u32_e32 v123, vcc, 0, v129, vcc
	v_add_co_u32_e32 v124, vcc, s20, v128
	s_nop 1
	v_addc_co_u32_e32 v125, vcc, 0, v129, vcc
	v_add_co_u32_e32 v130, vcc, s21, v128
	s_nop 1
	v_addc_co_u32_e32 v131, vcc, 0, v129, vcc
	v_add_co_u32_e32 v136, vcc, s22, v128
	s_nop 1
	v_addc_co_u32_e32 v137, vcc, 0, v129, vcc
	global_load_dwordx4 v[84:87], v[100:101], off
	global_load_dwordx4 v[88:91], v[102:103], off
	global_load_dwordx4 v[92:95], v[100:101], off offset:64
	global_load_dwordx4 v[96:99], v[102:103], off offset:64
	global_load_dwordx4 v[100:103], v[108:109], off
	global_load_dwordx4 v[104:107], v[108:109], off offset:64
	global_load_dwordx4 v[218:221], v[112:113], off
	global_load_dwordx4 v[108:111], v[112:113], off offset:64
	global_load_dwordx4 v[222:225], v[116:117], off
	global_load_dwordx4 v[112:115], v[116:117], off offset:64
	global_load_dwordx4 v[230:233], v[120:121], off
	global_load_dwordx4 v[116:119], v[120:121], off offset:64
	global_load_dwordx4 v[234:237], v[122:123], off
	global_load_dwordx4 v[120:123], v[122:123], off offset:64
	global_load_dwordx4 v[238:241], v[124:125], off
	global_load_dwordx4 v[124:127], v[124:125], off offset:64
	global_load_dwordx4 v[242:245], v[130:131], off
	global_load_dwordx4 v[128:131], v[130:131], off offset:64
	global_load_dwordx4 v[132:135], v[136:137], off
	global_load_dwordx4 v[246:249], v[136:137], off offset:64
	s_waitcnt vmcnt(18)
	v_mfma_f32_16x16x32_bf16 v[56:59], v[84:87], v[88:91], v[56:59]
	s_waitcnt vmcnt(15)
	v_mfma_f32_16x16x32_bf16 v[52:55], v[100:103], v[88:91], v[52:55]
	v_mfma_f32_16x16x32_bf16 v[56:59], v[92:95], v[96:99], v[56:59]
	s_waitcnt vmcnt(14)
	v_mfma_f32_16x16x32_bf16 v[52:55], v[104:107], v[96:99], v[52:55]
	s_waitcnt vmcnt(13)
	v_mfma_f32_16x16x32_bf16 v[44:47], v[84:87], v[218:221], v[44:47]
	v_mfma_f32_16x16x32_bf16 v[20:23], v[100:103], v[218:221], v[20:23]
	s_waitcnt vmcnt(12)
	v_mfma_f32_16x16x32_bf16 v[44:47], v[92:95], v[108:111], v[44:47]
	v_mfma_f32_16x16x32_bf16 v[20:23], v[104:107], v[108:111], v[20:23]
	s_waitcnt vmcnt(11)
	v_mfma_f32_16x16x32_bf16 v[12:15], v[84:87], v[222:225], v[12:15]
	v_mfma_f32_16x16x32_bf16 v[8:11], v[100:103], v[222:225], v[8:11]
	s_waitcnt vmcnt(10)
	v_mfma_f32_16x16x32_bf16 v[12:15], v[92:95], v[112:115], v[12:15]
	v_mfma_f32_16x16x32_bf16 v[8:11], v[104:107], v[112:115], v[8:11]
	s_waitcnt vmcnt(9)
	v_mfma_f32_16x16x32_bf16 v[4:7], v[84:87], v[230:233], v[4:7]
	v_mfma_f32_16x16x32_bf16 v[0:3], v[100:103], v[230:233], v[0:3]
	s_waitcnt vmcnt(8)
	v_mfma_f32_16x16x32_bf16 v[4:7], v[92:95], v[116:119], v[4:7]
	v_mfma_f32_16x16x32_bf16 v[0:3], v[104:107], v[116:119], v[0:3]
	s_waitcnt vmcnt(7)
	v_mfma_f32_16x16x32_bf16 v[16:19], v[84:87], v[234:237], v[16:19]
	v_mfma_f32_16x16x32_bf16 v[24:27], v[100:103], v[234:237], v[24:27]
	s_waitcnt vmcnt(6)
	v_mfma_f32_16x16x32_bf16 v[16:19], v[92:95], v[120:123], v[16:19]
	v_mfma_f32_16x16x32_bf16 v[24:27], v[104:107], v[120:123], v[24:27]
	s_waitcnt vmcnt(5)
	v_mfma_f32_16x16x32_bf16 v[28:31], v[84:87], v[238:241], v[28:31]
	v_mfma_f32_16x16x32_bf16 v[32:35], v[100:103], v[238:241], v[32:35]
	s_waitcnt vmcnt(4)
	v_mfma_f32_16x16x32_bf16 v[28:31], v[92:95], v[124:127], v[28:31]
	v_mfma_f32_16x16x32_bf16 v[32:35], v[104:107], v[124:127], v[32:35]
	s_waitcnt vmcnt(3)
	v_mfma_f32_16x16x32_bf16 v[36:39], v[84:87], v[242:245], v[36:39]
	v_mfma_f32_16x16x32_bf16 v[40:43], v[100:103], v[242:245], v[40:43]
	s_waitcnt vmcnt(1)
	v_mfma_f32_16x16x32_bf16 v[48:51], v[84:87], v[132:135], v[48:51]
	v_mfma_f32_16x16x32_bf16 v[60:63], v[100:103], v[132:135], v[60:63]
	v_mfma_f32_16x16x32_bf16 v[36:39], v[92:95], v[128:131], v[36:39]
	v_mfma_f32_16x16x32_bf16 v[40:43], v[104:107], v[128:131], v[40:43]
	s_waitcnt vmcnt(0)
	v_mfma_f32_16x16x32_bf16 v[48:51], v[92:95], v[246:249], v[48:51]
	v_mfma_f32_16x16x32_bf16 v[60:63], v[104:107], v[246:249], v[60:63]
	s_cbranch_scc0 .LBB0_522
	v_add_u32_e32 v68, s2, v77
	s_waitcnt lgkmcnt(0)
	s_barrier
	ds_write_b128 v68, v[56:59]
	ds_write_b128 v68, v[52:55] offset:1024
	ds_write_b128 v68, v[44:47] offset:2048
	ds_write_b128 v68, v[20:23] offset:3072
	ds_write_b128 v68, v[12:15] offset:4096
	ds_write_b128 v68, v[8:11] offset:5120
	ds_write_b128 v68, v[4:7] offset:6144
	ds_write_b128 v68, v[0:3] offset:7168
	ds_write_b128 v68, v[16:19] offset:8192
	ds_write_b128 v68, v[24:27] offset:9216
	ds_write_b128 v68, v[28:31] offset:10240
	ds_write_b128 v68, v[32:35] offset:11264
	ds_write_b128 v68, v[36:39] offset:12288
	ds_write_b128 v68, v[40:43] offset:13312
	ds_write_b128 v68, v[48:51] offset:14336
	ds_write_b128 v68, v[60:63] offset:15360
	s_waitcnt lgkmcnt(0)
	s_barrier
	global_load_dword v50, v[64:65], off
	v_add_u32_e32 v44, s3, v77
	v_add_u32_e32 v0, s3, v79
	v_add_u32_e32 v4, s3, v80
	v_add_u32_e32 v8, s3, v81
	v_add_u32_e32 v12, s3, v82
	ds_read_b128 v[0:3], v0
	ds_read_b128 v[4:7], v4
	ds_read_b128 v[8:11], v8
	ds_read_b128 v[12:15], v12
	ds_read_b128 v[16:19], v44
	ds_read_b128 v[20:23], v44 offset:1024
	ds_read_b128 v[24:27], v44 offset:16384
	ds_read_b128 v[28:31], v44 offset:17408
	ds_read_b128 v[32:35], v44 offset:32768
	ds_read_b128 v[36:39], v44 offset:33792
	ds_read_b128 v[40:43], v44 offset:49152
	ds_read_b128 v[44:47], v44 offset:50176
	s_waitcnt lgkmcnt(5)
	v_pk_add_f32 v[18:19], v[18:19], v[26:27]
	v_pk_add_f32 v[16:17], v[16:17], v[24:25]
	s_waitcnt lgkmcnt(3)
	v_pk_add_f32 v[18:19], v[18:19], v[34:35]
	v_pk_add_f32 v[16:17], v[16:17], v[32:33]
	s_waitcnt lgkmcnt(1)
	v_pk_add_f32 v[18:19], v[18:19], v[42:43]
	v_pk_add_f32 v[16:17], v[16:17], v[40:41]
	v_pk_add_f32 v[2:3], v[18:19], v[2:3]
	v_pk_add_f32 v[0:1], v[16:17], v[0:1]
	v_pk_add_f32 v[2:3], v[2:3], v[6:7]
	v_pk_add_f32 v[0:1], v[0:1], v[4:5]
	v_pk_add_f32 v[2:3], v[2:3], v[10:11]
	v_pk_add_f32 v[0:1], v[0:1], v[8:9]
	s_lshl_b32 s0, s24, 7
	v_pk_add_f32 v[2:3], v[2:3], v[14:15]
	v_pk_add_f32 v[0:1], v[0:1], v[12:13]
	s_sub_i32 s0, s23, s0
	v_max_f32_e32 v0, 0, v0
	v_max_f32_e32 v1, 0, v1
	v_max_f32_e32 v2, 0, v2
	v_max_f32_e32 v3, 0, v3
	v_lshl_or_b32 v48, s0, 5, v78
	v_pk_mul_f32 v[0:1], v[0:1], v[0:1]
	v_pk_mul_f32 v[2:3], v[2:3], v[2:3]
	v_ashrrev_i32_e32 v49, 31, v48
	v_lshl_add_u64 v[48:49], v[48:49], 1, v[66:67]
	v_add_u32_e32 v8, s4, v81
	v_add_u32_e32 v12, s4, v82
	v_pk_add_f32 v[16:17], v[22:23], v[30:31]
	v_pk_add_f32 v[18:19], v[20:21], v[28:29]
	v_pk_add_f32 v[16:17], v[16:17], v[38:39]
	v_pk_add_f32 v[18:19], v[18:19], v[36:37]
	s_waitcnt lgkmcnt(0)
	v_pk_add_f32 v[16:17], v[16:17], v[46:47]
	v_pk_add_f32 v[18:19], v[18:19], v[44:45]
	s_add_i32 s23, s23, s70
	s_cmpk_gt_i32 s23, 0x7f
	s_waitcnt vmcnt(0)
	v_mul_f32_e32 v4, v50, v50
	v_pk_mul_f32 v[0:1], v[4:5], v[0:1] op_sel_hi:[0,1]
	v_pk_mul_f32 v[2:3], v[4:5], v[2:3] op_sel_hi:[0,1]
	v_cvt_pk_bf16_f32 v0, v0, v1
	v_cvt_pk_bf16_f32 v1, v2, v3
	global_store_dwordx2 v[48:49], v[0:1], off
	global_load_dword v24, v[64:65], off
	v_add_u32_e32 v0, s4, v79
	v_add_u32_e32 v4, s4, v80
	ds_read_b128 v[0:3], v0
	ds_read_b128 v[4:7], v4
	ds_read_b128 v[8:11], v8
	ds_read_b128 v[12:15], v12
	s_waitcnt lgkmcnt(3)
	v_pk_add_f32 v[2:3], v[16:17], v[2:3]
	v_pk_add_f32 v[0:1], v[18:19], v[0:1]
	s_waitcnt lgkmcnt(2)
	v_pk_add_f32 v[2:3], v[2:3], v[6:7]
	v_pk_add_f32 v[0:1], v[0:1], v[4:5]
	s_waitcnt lgkmcnt(1)
	v_pk_add_f32 v[2:3], v[2:3], v[10:11]
	v_pk_add_f32 v[0:1], v[0:1], v[8:9]
	s_waitcnt lgkmcnt(0)
	v_pk_add_f32 v[2:3], v[2:3], v[14:15]
	v_pk_add_f32 v[0:1], v[0:1], v[12:13]
	v_max_f32_e32 v2, 0, v2
	v_max_f32_e32 v0, 0, v0
	v_max_f32_e32 v1, 0, v1
	v_max_f32_e32 v3, 0, v3
	v_pk_mul_f32 v[0:1], v[0:1], v[0:1]
	v_pk_mul_f32 v[2:3], v[2:3], v[2:3]
	s_waitcnt vmcnt(0)
	v_mul_f32_e32 v4, v24, v24
	v_pk_mul_f32 v[0:1], v[4:5], v[0:1] op_sel_hi:[0,1]
	v_pk_mul_f32 v[2:3], v[4:5], v[2:3] op_sel_hi:[0,1]
	v_cvt_pk_bf16_f32 v0, v0, v1
	v_cvt_pk_bf16_f32 v1, v2, v3
	global_store_dwordx2 v[48:49], v[0:1], off offset:32
	s_cbranch_scc0 .LBB0_521

.LBB0_580:
	v_lshl_add_u64 v[82:83], v[70:71], 0, s[2:3]
	v_add_co_u32_e32 v98, vcc, s9, v82
	v_lshl_add_u64 v[126:127], v[72:73], 0, s[2:3]
	s_nop 1
	v_addc_co_u32_e32 v99, vcc, 0, v83, vcc
	v_add_co_u32_e32 v106, vcc, s10, v82
	s_add_u32 s2, s2, 0x80
	s_nop 1
	v_addc_co_u32_e32 v107, vcc, 0, v83, vcc
	v_add_co_u32_e32 v100, vcc, s11, v126
	s_addc_u32 s3, s3, 0
	s_nop 1
	v_addc_co_u32_e32 v101, vcc, 0, v127, vcc
	v_add_co_u32_e32 v110, vcc, s18, v126
	s_cmpk_eq_i32 s2, 0x100
	s_nop 1
	v_addc_co_u32_e32 v111, vcc, 0, v127, vcc
	v_add_co_u32_e32 v114, vcc, s19, v126
	s_nop 1
	v_addc_co_u32_e32 v115, vcc, 0, v127, vcc
	v_add_co_u32_e32 v118, vcc, s20, v126
	s_nop 1
	v_addc_co_u32_e32 v119, vcc, 0, v127, vcc
	v_add_co_u32_e32 v120, vcc, s21, v126
	s_nop 1
	v_addc_co_u32_e32 v121, vcc, 0, v127, vcc
	v_add_co_u32_e32 v122, vcc, s22, v126
	s_nop 1
	v_addc_co_u32_e32 v123, vcc, 0, v127, vcc
	v_add_co_u32_e32 v128, vcc, s23, v126
	s_nop 1
	v_addc_co_u32_e32 v129, vcc, 0, v127, vcc
	v_add_co_u32_e32 v134, vcc, s25, v126
	s_nop 1
	v_addc_co_u32_e32 v135, vcc, 0, v127, vcc
	global_load_dwordx4 v[82:85], v[98:99], off
	global_load_dwordx4 v[86:89], v[100:101], off
	global_load_dwordx4 v[90:93], v[98:99], off offset:64
	global_load_dwordx4 v[94:97], v[100:101], off offset:64
	global_load_dwordx4 v[98:101], v[106:107], off
	global_load_dwordx4 v[102:105], v[106:107], off offset:64
	global_load_dwordx4 v[188:191], v[110:111], off
	global_load_dwordx4 v[106:109], v[110:111], off offset:64
	global_load_dwordx4 v[222:225], v[114:115], off
	global_load_dwordx4 v[110:113], v[114:115], off offset:64
	global_load_dwordx4 v[230:233], v[118:119], off
	global_load_dwordx4 v[114:117], v[118:119], off offset:64
	global_load_dwordx4 v[234:237], v[120:121], off
	global_load_dwordx4 v[118:121], v[120:121], off offset:64
	global_load_dwordx4 v[238:241], v[122:123], off
	global_load_dwordx4 v[122:125], v[122:123], off offset:64
	global_load_dwordx4 v[242:245], v[128:129], off
	global_load_dwordx4 v[126:129], v[128:129], off offset:64
	global_load_dwordx4 v[130:133], v[134:135], off
	global_load_dwordx4 v[246:249], v[134:135], off offset:64
	s_waitcnt vmcnt(18)
	v_mfma_f32_16x16x32_bf16 v[56:59], v[82:85], v[86:89], v[56:59]
	s_waitcnt vmcnt(15)
	v_mfma_f32_16x16x32_bf16 v[52:55], v[98:101], v[86:89], v[52:55]
	v_mfma_f32_16x16x32_bf16 v[56:59], v[90:93], v[94:97], v[56:59]
	s_waitcnt vmcnt(14)
	v_mfma_f32_16x16x32_bf16 v[52:55], v[102:105], v[94:97], v[52:55]
	s_waitcnt vmcnt(13)
	v_mfma_f32_16x16x32_bf16 v[44:47], v[82:85], v[188:191], v[44:47]
	v_mfma_f32_16x16x32_bf16 v[20:23], v[98:101], v[188:191], v[20:23]
	s_waitcnt vmcnt(12)
	v_mfma_f32_16x16x32_bf16 v[44:47], v[90:93], v[106:109], v[44:47]
	v_mfma_f32_16x16x32_bf16 v[20:23], v[102:105], v[106:109], v[20:23]
	s_waitcnt vmcnt(11)
	v_mfma_f32_16x16x32_bf16 v[12:15], v[82:85], v[222:225], v[12:15]
	v_mfma_f32_16x16x32_bf16 v[8:11], v[98:101], v[222:225], v[8:11]
	s_waitcnt vmcnt(10)
	v_mfma_f32_16x16x32_bf16 v[12:15], v[90:93], v[110:113], v[12:15]
	v_mfma_f32_16x16x32_bf16 v[8:11], v[102:105], v[110:113], v[8:11]
	s_waitcnt vmcnt(9)
	v_mfma_f32_16x16x32_bf16 v[4:7], v[82:85], v[230:233], v[4:7]
	v_mfma_f32_16x16x32_bf16 v[0:3], v[98:101], v[230:233], v[0:3]
	s_waitcnt vmcnt(8)
	v_mfma_f32_16x16x32_bf16 v[4:7], v[90:93], v[114:117], v[4:7]
	v_mfma_f32_16x16x32_bf16 v[0:3], v[102:105], v[114:117], v[0:3]
	s_waitcnt vmcnt(7)
	v_mfma_f32_16x16x32_bf16 v[16:19], v[82:85], v[234:237], v[16:19]
	v_mfma_f32_16x16x32_bf16 v[24:27], v[98:101], v[234:237], v[24:27]
	s_waitcnt vmcnt(6)
	v_mfma_f32_16x16x32_bf16 v[16:19], v[90:93], v[118:121], v[16:19]
	v_mfma_f32_16x16x32_bf16 v[24:27], v[102:105], v[118:121], v[24:27]
	s_waitcnt vmcnt(5)
	v_mfma_f32_16x16x32_bf16 v[28:31], v[82:85], v[238:241], v[28:31]
	v_mfma_f32_16x16x32_bf16 v[32:35], v[98:101], v[238:241], v[32:35]
	s_waitcnt vmcnt(4)
	v_mfma_f32_16x16x32_bf16 v[28:31], v[90:93], v[122:125], v[28:31]
	v_mfma_f32_16x16x32_bf16 v[32:35], v[102:105], v[122:125], v[32:35]
	s_waitcnt vmcnt(3)
	v_mfma_f32_16x16x32_bf16 v[36:39], v[82:85], v[242:245], v[36:39]
	v_mfma_f32_16x16x32_bf16 v[40:43], v[98:101], v[242:245], v[40:43]
	s_waitcnt vmcnt(1)
	v_mfma_f32_16x16x32_bf16 v[48:51], v[82:85], v[130:133], v[48:51]
	v_mfma_f32_16x16x32_bf16 v[60:63], v[98:101], v[130:133], v[60:63]
	v_mfma_f32_16x16x32_bf16 v[36:39], v[90:93], v[126:129], v[36:39]
	v_mfma_f32_16x16x32_bf16 v[40:43], v[102:105], v[126:129], v[40:43]
	s_waitcnt vmcnt(0)
	v_mfma_f32_16x16x32_bf16 v[48:51], v[90:93], v[246:249], v[48:51]
	v_mfma_f32_16x16x32_bf16 v[60:63], v[102:105], v[246:249], v[60:63]
	s_cbranch_scc0 .LBB0_580
	v_add_u32_e32 v66, s6, v75
	s_waitcnt lgkmcnt(0)
	s_barrier
	ds_write_b128 v66, v[56:59]
	ds_write_b128 v66, v[52:55] offset:1024
	ds_write_b128 v66, v[44:47] offset:2048
	ds_write_b128 v66, v[20:23] offset:3072
	ds_write_b128 v66, v[12:15] offset:4096
	ds_write_b128 v66, v[8:11] offset:5120
	ds_write_b128 v66, v[4:7] offset:6144
	ds_write_b128 v66, v[0:3] offset:7168
	ds_write_b128 v66, v[16:19] offset:8192
	ds_write_b128 v66, v[24:27] offset:9216
	ds_write_b128 v66, v[28:31] offset:10240
	ds_write_b128 v66, v[32:35] offset:11264
	ds_write_b128 v66, v[36:39] offset:12288
	ds_write_b128 v66, v[40:43] offset:13312
	ds_write_b128 v66, v[48:51] offset:14336
	ds_write_b128 v66, v[60:63] offset:15360
	s_waitcnt lgkmcnt(0)
	s_barrier
	v_add_u32_e32 v22, s7, v75
	ds_read_b128 v[0:3], v22
	ds_read_b128 v[4:7], v22 offset:16384
	ds_read_b128 v[8:11], v22 offset:32768
	ds_read_b128 v[12:15], v22 offset:1024
	ds_read_b128 v[16:19], v22 offset:17408
	s_lshl_b32 s1, s0, 5
	s_sub_i32 s1, s5, s1
	v_lshl_or_b32 v28, s1, 5, v76
	s_waitcnt lgkmcnt(3)
	v_pk_add_f32 v[6:7], v[2:3], v[6:7]
	v_pk_add_f32 v[20:21], v[0:1], v[4:5]
	ds_read_b128 v[0:3], v22 offset:33792
	s_waitcnt lgkmcnt(3)
	v_pk_add_f32 v[24:25], v[6:7], v[10:11]
	ds_read_b128 v[4:7], v22 offset:49152
	v_pk_add_f32 v[26:27], v[20:21], v[8:9]
	v_add_u32_e32 v8, s7, v77
	ds_read_b128 v[8:11], v8
	ds_read_b128 v[20:23], v22 offset:50176
	s_ashr_i32 s1, s0, 31
	s_waitcnt lgkmcnt(2)
	v_pk_add_f32 v[26:27], v[26:27], v[4:5]
	v_add_u32_e32 v4, s7, v78
	v_pk_add_f32 v[24:25], v[24:25], v[6:7]
	ds_read_b128 v[4:7], v4
	s_waitcnt lgkmcnt(2)
	v_pk_add_f32 v[34:35], v[26:27], v[8:9]
	v_add_u32_e32 v8, s7, v79
	v_pk_add_f32 v[32:33], v[24:25], v[10:11]
	ds_read_b128 v[8:11], v8
	v_add_u32_e32 v24, s7, v80
	ds_read_b128 v[24:27], v24
	s_lshl_b64 s[0:1], s[0:1], 19
	s_waitcnt lgkmcnt(2)
	v_pk_add_f32 v[6:7], v[32:33], v[6:7]
	v_pk_add_f32 v[4:5], v[34:35], v[4:5]
	v_lshl_add_u64 v[30:31], v[64:65], 0, s[0:1]
	s_waitcnt lgkmcnt(1)
	v_pk_add_f32 v[6:7], v[6:7], v[10:11]
	v_pk_add_f32 v[4:5], v[4:5], v[8:9]
	v_ashrrev_i32_e32 v29, 31, v28
	s_waitcnt lgkmcnt(0)
	v_pk_add_f32 v[6:7], v[6:7], v[26:27]
	v_pk_add_f32 v[4:5], v[4:5], v[24:25]
	v_lshl_add_u64 v[24:25], v[28:29], 2, v[30:31]
	global_store_dwordx4 v[24:25], v[4:7], off
	s_add_i32 s5, s5, s4
	s_cmpk_gt_i32 s5, 0x7f
	v_pk_add_f32 v[6:7], v[12:13], v[16:17]
	v_pk_add_f32 v[4:5], v[14:15], v[18:19]
	v_pk_add_f32 v[6:7], v[6:7], v[0:1]
	v_add_u32_e32 v0, s8, v77
	v_pk_add_f32 v[4:5], v[4:5], v[2:3]
	ds_read_b128 v[0:3], v0
	v_pk_add_f32 v[8:9], v[4:5], v[22:23]
	v_pk_add_f32 v[10:11], v[6:7], v[20:21]
	v_add_u32_e32 v4, s8, v78
	ds_read_b128 v[4:7], v4
	s_waitcnt lgkmcnt(1)
	v_pk_add_f32 v[14:15], v[10:11], v[0:1]
	v_add_u32_e32 v0, s8, v79
	v_pk_add_f32 v[12:13], v[8:9], v[2:3]
	ds_read_b128 v[0:3], v0
	v_add_u32_e32 v8, s8, v80
	ds_read_b128 v[8:11], v8
	s_waitcnt lgkmcnt(2)
	v_pk_add_f32 v[6:7], v[12:13], v[6:7]
	v_pk_add_f32 v[4:5], v[14:15], v[4:5]
	s_waitcnt lgkmcnt(1)
	v_pk_add_f32 v[2:3], v[6:7], v[2:3]
	v_pk_add_f32 v[0:1], v[4:5], v[0:1]
	s_waitcnt lgkmcnt(0)
	v_pk_add_f32 v[2:3], v[2:3], v[10:11]
	v_pk_add_f32 v[0:1], v[0:1], v[8:9]
	global_store_dwordx4 v[24:25], v[0:3], off offset:64
	s_cbranch_scc0 .LBB0_579
